# v28 + second LayerNorm phase (ffn LN of layer 0) with the same gamma/beta hoist and next-row prefetch
# speedup vs baseline: 1.0177x; 1.0010x over previous
.LBB0_722:
	s_or_b64 exec, exec, s[0:1]
	v_mov_b32_e32 v4, v160
	s_and_b64 vcc, exec, s[70:71]
	s_waitcnt lgkmcnt(0)
	s_barrier
	s_cbranch_vccz .LBB0_726
	v_mbcnt_hi_u32_b32 v0, -1, v186
	v_and_b32_e32 v1, 64, v0
	v_add_u32_e32 v1, 64, v1
	v_xor_b32_e32 v2, 1, v0
	v_cmp_lt_i32_e32 vcc, v2, v1
	s_ashr_i32 s47, s46, 31
	v_ashrrev_i32_e32 v5, 31, v4
	v_cndmask_b32_e32 v2, v0, v2, vcc
	v_lshlrev_b32_e32 v8, 2, v2
	v_xor_b32_e32 v2, 2, v0
	v_cmp_lt_i32_e32 vcc, v2, v1
	v_readlane_b32 s12, v234, 23
	s_lshl_b64 s[0:1], s[46:47], 11
	v_cndmask_b32_e32 v2, v0, v2, vcc
	v_lshlrev_b32_e32 v9, 2, v2
	v_xor_b32_e32 v2, 4, v0
	v_cmp_lt_i32_e32 vcc, v2, v1
	v_lshlrev_b64 v[6:7], 4, v[4:5]
	v_readlane_b32 s13, v234, 24
	v_cndmask_b32_e32 v2, v0, v2, vcc
	v_lshlrev_b32_e32 v10, 2, v2
	v_xor_b32_e32 v2, 8, v0
	v_cmp_lt_i32_e32 vcc, v2, v1
	v_readlane_b32 s14, v234, 25
	v_readlane_b32 s15, v234, 26
	v_cndmask_b32_e32 v2, v0, v2, vcc
	v_lshlrev_b32_e32 v11, 2, v2
	v_xor_b32_e32 v2, 16, v0
	v_cmp_lt_i32_e32 vcc, v2, v1
	v_lshl_add_u64 v[4:5], v[4:5], 3, s[0:1]
	s_ashr_i32 s81, s80, 31
	v_cndmask_b32_e32 v2, v0, v2, vcc
	v_lshlrev_b32_e32 v12, 2, v2
	v_xor_b32_e32 v2, 32, v0
	v_cmp_lt_i32_e32 vcc, v2, v1
	s_lshl_b64 s[0:1], s[46:47], 12
	s_lshl_b64 s[4:5], s[80:81], 11
	v_cndmask_b32_e32 v0, v0, v2, vcc
	v_lshlrev_b32_e32 v13, 2, v0
	v_lshl_add_u64 v[0:1], s[12:13], 0, v[6:7]
	v_lshl_add_u64 v[2:3], s[14:15], 0, v[6:7]
	v_lshl_add_u64 v[6:7], s[0:1], 0, v[6:7]
	s_lshl_b64 s[6:7], s[80:81], 12
	s_mov_b32 s8, 0x3fb504f3
	v_mov_b32_e32 v14, 0x3727c5ac
	s_mov_b32 s3, 0xf800000
	v_mov_b32_e32 v15, 0x260
	s_mov_b32 s9, 0xe400000
	s_mov_b32 s10, s46
	v_readlane_b32 s16, v234, 27
	v_readlane_b32 s17, v234, 28
	v_readlane_b32 s18, v234, 29
	v_readlane_b32 s19, v234, 30
	v_readlane_b32 s20, v234, 31
	v_readlane_b32 s21, v234, 32
	v_readlane_b32 s22, v234, 33
	v_readlane_b32 s23, v234, 34
	v_readlane_b32 s24, v234, 35
	v_readlane_b32 s25, v234, 36
	v_readlane_b32 s26, v234, 37
	v_readlane_b32 s27, v234, 38
	global_load_dwordx4 v[64:67], v[0:1], off
	global_load_dwordx4 v[68:71], v[0:1], off offset:1024
	global_load_dwordx4 v[72:75], v[0:1], off offset:2048
	global_load_dwordx4 v[76:79], v[0:1], off offset:3072
	global_load_dwordx4 v[80:83], v[2:3], off
	global_load_dwordx4 v[84:87], v[2:3], off offset:1024
	global_load_dwordx4 v[88:91], v[2:3], off offset:2048
	global_load_dwordx4 v[92:95], v[2:3], off offset:3072
	s_add_u32 s98, s84, 0x14400000
	s_addc_u32 s99, s85, 0
	s_add_u32 s100, s84, 0x10400000
	s_addc_u32 s101, s85, 0
	v_lshl_add_u64 v[124:125], s[100:101], 0, v[6:7]
	v_lshl_add_u64 v[126:127], s[98:99], 0, v[4:5]
	global_load_dwordx4 v[100:103], v[124:125], off nt
	global_load_dwordx4 v[104:107], v[124:125], off offset:1024 nt
	global_load_dwordx4 v[108:111], v[124:125], off offset:2048 nt
	global_load_dwordx4 v[112:115], v[124:125], off offset:3072 nt
	global_load_dwordx2 v[116:117], v[126:127], off nt
	global_load_dwordx2 v[118:119], v[126:127], off offset:512 nt
	global_load_dwordx2 v[120:121], v[126:127], off offset:1024 nt
	global_load_dwordx2 v[122:123], v[126:127], off offset:1536 nt
	s_waitcnt vmcnt(0)
.LBB0_724:
	s_waitcnt vmcnt(8)
	v_lshl_add_u64 v[42:43], s[100:101], 0, v[6:7]
	v_lshl_add_u64 v[26:27], s[84:85], 0, v[4:5]
	v_add_co_u32_e64 v40, s[0:1], s9, v26
	s_add_i32 s10, s10, s80
	v_lshl_add_u64 v[4:5], v[4:5], 0, s[4:5]
	v_lshl_add_u64 v[6:7], v[6:7], 0, s[6:7]
	v_addc_co_u32_e64 v41, s[0:1], 0, v27, s[0:1]
	s_cmpk_lt_i32 s10, 0x4000
	v_lshlrev_b32_e32 v52, 16, v116
	v_and_b32_e32 v53, 0xffff0000, v116
	v_lshlrev_b32_e32 v44, 16, v117
	v_and_b32_e32 v45, 0xffff0000, v117
	v_lshlrev_b32_e32 v54, 16, v118
	v_and_b32_e32 v55, 0xffff0000, v118
	v_lshlrev_b32_e32 v46, 16, v119
	v_and_b32_e32 v47, 0xffff0000, v119
	v_lshlrev_b32_e32 v56, 16, v120
	v_and_b32_e32 v57, 0xffff0000, v120
	v_lshlrev_b32_e32 v48, 16, v121
	v_and_b32_e32 v49, 0xffff0000, v121
	v_lshlrev_b32_e32 v58, 16, v122
	v_and_b32_e32 v59, 0xffff0000, v122
	v_lshlrev_b32_e32 v50, 16, v123
	v_and_b32_e32 v51, 0xffff0000, v123
	v_pk_fma_f32 v[26:27], v[102:103], s[8:9], v[44:45] op_sel_hi:[1,0,1]
	v_pk_fma_f32 v[24:25], v[100:101], s[8:9], v[52:53] op_sel_hi:[1,0,1]
	v_pk_fma_f32 v[30:31], v[106:107], s[8:9], v[46:47] op_sel_hi:[1,0,1]
	v_pk_fma_f32 v[28:29], v[104:105], s[8:9], v[54:55] op_sel_hi:[1,0,1]
	v_pk_fma_f32 v[34:35], v[110:111], s[8:9], v[48:49] op_sel_hi:[1,0,1]
	v_pk_fma_f32 v[38:39], v[114:115], s[8:9], v[50:51] op_sel_hi:[1,0,1]
	v_pk_fma_f32 v[32:33], v[108:109], s[8:9], v[56:57] op_sel_hi:[1,0,1]
	v_pk_fma_f32 v[36:37], v[112:113], s[8:9], v[58:59] op_sel_hi:[1,0,1]
	s_cbranch_scc0 .Lln8_skip
	v_lshl_add_u64 v[124:125], s[100:101], 0, v[6:7]
	v_lshl_add_u64 v[126:127], s[98:99], 0, v[4:5]
	global_load_dwordx4 v[100:103], v[124:125], off nt
	global_load_dwordx4 v[104:107], v[124:125], off offset:1024 nt
	global_load_dwordx4 v[108:111], v[124:125], off offset:2048 nt
	global_load_dwordx4 v[112:115], v[124:125], off offset:3072 nt
	global_load_dwordx2 v[116:117], v[126:127], off nt
	global_load_dwordx2 v[118:119], v[126:127], off offset:512 nt
	global_load_dwordx2 v[120:121], v[126:127], off offset:1024 nt
	global_load_dwordx2 v[122:123], v[126:127], off offset:1536 nt
.Lln8_skip:
	v_pk_mov_b32 v[44:45], v[24:25], v[26:27] op_sel:[1,0]
	v_mov_b32_e32 v46, v24
	v_mov_b32_e32 v47, v27
	v_pk_mov_b32 v[48:49], v[28:29], v[30:31] op_sel:[1,0]
	v_mov_b32_e32 v50, v28
	v_mov_b32_e32 v51, v31
	v_pk_add_f32 v[44:45], v[44:45], v[46:47]
	v_pk_add_f32 v[46:47], v[48:49], v[50:51]
	v_add_f32_e32 v50, v44, v45
	v_pk_add_f32 v[44:45], v[46:47], v[46:47] op_sel:[0,1] op_sel_hi:[1,0]
	v_add_f32_e32 v52, v32, v33
	v_add_f32_e32 v54, v34, v35
	v_mov_b32_e32 v57, v36
	v_mov_b32_e32 v53, v38
	v_mov_b32_e32 v55, v39
	v_add_f32_e32 v56, 0, v50
	v_mov_b32_e32 v45, v37
	v_pk_add_f32 v[48:49], v[52:53], v[54:55]
	v_pk_add_f32 v[44:45], v[56:57], v[44:45]
	s_nop 0
	v_pk_add_f32 v[44:45], v[44:45], v[48:49]
	s_nop 0
	v_add_f32_e32 v44, v44, v45
	ds_bpermute_b32 v45, v8, v44
	s_waitcnt lgkmcnt(0)
	v_add_f32_e32 v44, v44, v45
	ds_bpermute_b32 v45, v9, v44
	s_waitcnt lgkmcnt(0)
	v_add_f32_e32 v44, v44, v45
	ds_bpermute_b32 v45, v10, v44
	s_waitcnt lgkmcnt(0)
	v_add_f32_e32 v44, v44, v45
	ds_bpermute_b32 v45, v11, v44
	s_waitcnt lgkmcnt(0)
	v_add_f32_e32 v44, v44, v45
	ds_bpermute_b32 v45, v12, v44
	s_waitcnt lgkmcnt(0)
	v_add_f32_e32 v44, v44, v45
	ds_bpermute_b32 v45, v13, v44
	s_waitcnt lgkmcnt(0)
	v_add_f32_e32 v44, v44, v45
	v_fmamk_f32 v25, v44, 0xba800000, v25
	v_fmac_f32_e32 v24, 0xba800000, v44
	v_fmamk_f32 v27, v44, 0xba800000, v27
	v_fmac_f32_e32 v26, 0xba800000, v44
	v_fmamk_f32 v29, v44, 0xba800000, v29
	v_fmac_f32_e32 v28, 0xba800000, v44
	v_fmamk_f32 v31, v44, 0xba800000, v31
	v_fmac_f32_e32 v30, 0xba800000, v44
	v_fmamk_f32 v33, v44, 0xba800000, v33
	v_fmac_f32_e32 v32, 0xba800000, v44
	v_fmamk_f32 v35, v44, 0xba800000, v35
	v_fmac_f32_e32 v34, 0xba800000, v44
	v_fmamk_f32 v39, v44, 0xba800000, v39
	v_fmac_f32_e32 v38, 0xba800000, v44
	v_fmamk_f32 v37, v44, 0xba800000, v37
	v_fmac_f32_e32 v36, 0xba800000, v44
	v_pk_mul_f32 v[44:45], v[26:27], v[26:27]
	v_pk_mul_f32 v[46:47], v[24:25], v[24:25]
	v_pk_mul_f32 v[48:49], v[30:31], v[30:31]
	v_pk_mul_f32 v[50:51], v[28:29], v[28:29]
	v_pk_mov_b32 v[56:57], v[46:47], v[44:45] op_sel:[1,0]
	v_mov_b32_e32 v47, v45
	v_pk_mov_b32 v[44:45], v[50:51], v[48:49] op_sel:[1,0]
	v_mov_b32_e32 v51, v49
	v_mul_f32_e32 v52, v32, v32
	v_mul_f32_e32 v54, v34, v34
	v_pk_add_f32 v[46:47], v[56:57], v[46:47]
	v_pk_add_f32 v[44:45], v[44:45], v[50:51]
	v_pk_fma_f32 v[48:49], v[32:33], v[32:33], v[52:53] op_sel_hi:[1,1,0]
	v_pk_fma_f32 v[52:53], v[34:35], v[34:35], v[54:55] op_sel_hi:[1,1,0]
	v_pk_add_f32 v[46:47], v[46:47], v[46:47] op_sel_hi:[0,1]
	v_pk_add_f32 v[44:45], v[44:45], v[44:45] op_sel_hi:[0,1]
	v_mul_f32_e32 v48, v36, v36
	v_mul_f32_e32 v52, v37, v37
	v_mul_f32_e32 v46, v38, v38
	v_mul_f32_e32 v44, v39, v39
	v_pk_add_f32 v[48:49], v[48:49], v[52:53]
	v_pk_add_f32 v[44:45], v[46:47], v[44:45]
	s_nop 0
	v_pk_add_f32 v[44:45], v[48:49], v[44:45]
	s_nop 0
	v_add_f32_e32 v44, v44, v45
	ds_bpermute_b32 v45, v8, v44
	s_waitcnt lgkmcnt(0)
	v_add_f32_e32 v44, v44, v45
	ds_bpermute_b32 v45, v9, v44
	s_waitcnt lgkmcnt(0)
	v_add_f32_e32 v44, v44, v45
	ds_bpermute_b32 v45, v10, v44
	s_waitcnt lgkmcnt(0)
	v_add_f32_e32 v44, v44, v45
	ds_bpermute_b32 v45, v11, v44
	s_waitcnt lgkmcnt(0)
	v_add_f32_e32 v44, v44, v45
	ds_bpermute_b32 v45, v12, v44
	s_waitcnt lgkmcnt(0)
	v_add_f32_e32 v44, v44, v45
	ds_bpermute_b32 v45, v13, v44
	s_waitcnt lgkmcnt(0)
	v_add_f32_e32 v44, v44, v45
	v_fmamk_f32 v44, v44, 0x3a800000, v14
	v_mul_f32_e32 v45, 0x4f800000, v44
	v_cmp_gt_f32_e32 vcc, s3, v44
	s_nop 1
	v_cndmask_b32_e32 v44, v44, v45, vcc
	v_sqrt_f32_e32 v45, v44
	s_nop 0
	v_add_u32_e32 v46, -1, v45
	v_add_u32_e32 v47, 1, v45
	v_fma_f32 v48, -v46, v45, v44
	v_fma_f32 v49, -v47, v45, v44
	v_cmp_ge_f32_e64 s[0:1], 0, v48
	s_nop 1
	v_cndmask_b32_e64 v45, v45, v46, s[0:1]
	v_cmp_lt_f32_e64 s[0:1], 0, v49
	s_nop 1
	v_cndmask_b32_e64 v45, v45, v47, s[0:1]
	v_mul_f32_e32 v46, 0x37800000, v45
	v_cndmask_b32_e32 v45, v45, v46, vcc
	v_cmp_class_f32_e32 vcc, v44, v15
	s_nop 1
	v_cndmask_b32_e32 v44, v45, v44, vcc
	v_div_scale_f32 v45, s[0:1], v44, v44, 1.0
	v_rcp_f32_e32 v47, v45
	v_div_scale_f32 v46, vcc, 1.0, v44, 1.0
	v_fma_f32 v48, -v45, v47, 1.0
	v_fmac_f32_e32 v47, v48, v47
	v_mul_f32_e32 v48, v46, v47
	v_fma_f32 v49, -v45, v48, v46
	v_fmac_f32_e32 v48, v49, v47
	v_fma_f32 v45, -v45, v48, v46
	v_div_fmas_f32 v45, v45, v47, v48
	v_div_fixup_f32 v44, v45, v44, 1.0
	v_pk_mul_f32 v[24:25], v[24:25], v[44:45] op_sel_hi:[1,0]
	v_pk_mul_f32 v[26:27], v[26:27], v[44:45] op_sel_hi:[1,0]
	v_pk_fma_f32 v[16:17], v[64:65], v[24:25], v[80:81]
	v_pk_fma_f32 v[18:19], v[66:67], v[26:27], v[82:83]
	global_store_dwordx4 v[42:43], v[16:19], off nt
	v_pk_mul_f32 v[24:25], v[30:31], v[44:45] op_sel_hi:[1,0]
	v_pk_mul_f32 v[26:27], v[28:29], v[44:45] op_sel_hi:[1,0]
	v_cvt_pk_bf16_f32 v16, v16, v17
	v_cvt_pk_bf16_f32 v17, v18, v19
	global_store_dwordx2 v[40:41], v[16:17], off
	s_nop 0
	v_pk_fma_f32 v[16:17], v[68:69], v[26:27], v[84:85]
	v_pk_fma_f32 v[18:19], v[70:71], v[24:25], v[86:87]
	global_store_dwordx4 v[42:43], v[16:19], off offset:1024 nt
	v_pk_mul_f32 v[24:25], v[34:35], v[44:45] op_sel_hi:[1,0]
	v_pk_mul_f32 v[26:27], v[32:33], v[44:45] op_sel_hi:[1,0]
	v_cvt_pk_bf16_f32 v16, v16, v17
	v_cvt_pk_bf16_f32 v17, v18, v19
	global_store_dwordx2 v[40:41], v[16:17], off offset:512
	s_nop 0
	v_pk_fma_f32 v[16:17], v[72:73], v[26:27], v[88:89]
	v_pk_fma_f32 v[18:19], v[74:75], v[24:25], v[90:91]
	global_store_dwordx4 v[42:43], v[16:19], off offset:2048 nt
	v_pk_mul_f32 v[24:25], v[38:39], v[44:45] op_sel_hi:[1,0]
	v_pk_mul_f32 v[26:27], v[36:37], v[44:45] op_sel_hi:[1,0]
	v_cvt_pk_bf16_f32 v16, v16, v17
	v_cvt_pk_bf16_f32 v17, v18, v19
	global_store_dwordx2 v[40:41], v[16:17], off offset:1024
	s_nop 0
	v_pk_fma_f32 v[16:17], v[76:77], v[26:27], v[92:93]
	v_pk_fma_f32 v[18:19], v[78:79], v[24:25], v[94:95]
	global_store_dwordx4 v[42:43], v[16:19], off offset:3072 nt
	s_nop 1
	v_cvt_pk_bf16_f32 v16, v16, v17
	v_cvt_pk_bf16_f32 v17, v18, v19
	global_store_dwordx2 v[40:41], v[16:17], off offset:1536
	s_cbranch_scc1 .LBB0_724
	v_readlane_b32 s81, v234, 49
